# skinny sample-row GEMMs rewritten by hand: all 256 CUs (64-row half tiles, XCD-paired), deep B/A prefetch, same K split
# speedup vs baseline: 1.0266x; 1.0266x over previous
.LBB0_687:
	s_waitcnt vmcnt(0)
	s_barrier
	v_and_b32_e32 v23, 63, v172
	v_and_b32_e32 v21, 15, v172
	v_bfe_u32 v22, v172, 4, 2
	v_readfirstlane_b32 s20, v172
	s_add_u32 s0, s92, 0x1e800000
	s_addc_u32 s1, s93, 0
	s_add_u32 s2, s92, 0x1c00000
	s_addc_u32 s3, s93, 0
	s_lshr_b32 s13, s20, 6
	s_mov_b32 s12, s76
	s_add_u32 s4, s92, 0x8000
	s_addc_u32 s5, s93, 0
	v_readlane_b32 s6, v237, 14
	v_readlane_b32 s7, v237, 15
	s_add_u32 s8, s92, 0x9200000
	s_addc_u32 s9, s93, 0
.Lsk_p3_loop:
	s_cmpk_lt_i32 s12, 0x100
	s_cbranch_scc0 .Lsk_p3_done
	s_and_b32 s18, s12, 7
	s_lshr_b32 s20, s12, 4
	s_lshl_b32 s20, s20, 3
	s_or_b32 s18, s18, s20
	s_bfe_u32 s19, s12, 0x10003
	s_lshl_b32 s20, s19, 6
	v_add_u32_e32 v28, s20, v21
	s_mul_i32 s21, s13, 0x300
	v_mul_u32_u24_e32 v16, 0x1800, v28
	v_add_u32_e32 v16, s21, v16
	v_lshl_add_u32 v16, v22, 4, v16
	v_add_u32_e32 v17, 0x18000, v16
	v_add_u32_e32 v18, 0x30000, v16
	v_add_u32_e32 v19, 0x48000, v16
	s_lshl_b32 s20, s18, 4
	v_add_u32_e32 v29, s20, v21
	v_mul_u32_u24_e32 v20, 0x1800, v29
	v_add_u32_e32 v20, s21, v20
	v_lshl_add_u32 v20, v22, 4, v20
	v_lshlrev_b32_e32 v30, 2, v28
	global_load_dword v24, v30, s[4:5] offset:0
	global_load_dword v25, v30, s[4:5] offset:64
	global_load_dword v26, v30, s[4:5] offset:128
	global_load_dword v27, v30, s[4:5] offset:192
	global_load_dwordx4 v[32:35], v20, s[2:3] offset:0
	global_load_dwordx4 v[36:39], v20, s[2:3] offset:64
	global_load_dwordx4 v[40:43], v20, s[2:3] offset:128
	global_load_dwordx4 v[44:47], v20, s[2:3] offset:192
	global_load_dwordx4 v[48:51], v20, s[2:3] offset:256
	global_load_dwordx4 v[52:55], v20, s[2:3] offset:320
	global_load_dwordx4 v[56:59], v20, s[2:3] offset:384
	global_load_dwordx4 v[60:63], v20, s[2:3] offset:448
	global_load_dwordx4 v[64:67], v20, s[2:3] offset:512
	global_load_dwordx4 v[68:71], v20, s[2:3] offset:576
	global_load_dwordx4 v[72:75], v20, s[2:3] offset:640
	global_load_dwordx4 v[76:79], v20, s[2:3] offset:704
	global_load_dwordx4 v[80:83], v16, s[0:1] offset:0
	global_load_dwordx4 v[84:87], v17, s[0:1] offset:0
	global_load_dwordx4 v[88:91], v18, s[0:1] offset:0
	global_load_dwordx4 v[92:95], v19, s[0:1] offset:0
	global_load_dwordx4 v[96:99], v16, s[0:1] offset:64
	global_load_dwordx4 v[100:103], v17, s[0:1] offset:64
	global_load_dwordx4 v[104:107], v18, s[0:1] offset:64
	global_load_dwordx4 v[108:111], v19, s[0:1] offset:64
	global_load_dwordx4 v[112:115], v16, s[0:1] offset:128
	global_load_dwordx4 v[116:119], v17, s[0:1] offset:128
	global_load_dwordx4 v[120:123], v18, s[0:1] offset:128
	global_load_dwordx4 v[124:127], v19, s[0:1] offset:128
	global_load_dwordx4 v[174:177], v16, s[0:1] offset:192
	global_load_dwordx4 v[178:181], v17, s[0:1] offset:192
	global_load_dwordx4 v[182:185], v18, s[0:1] offset:192
	global_load_dwordx4 v[186:189], v19, s[0:1] offset:192
	global_load_dwordx4 v[190:193], v16, s[0:1] offset:256
	global_load_dwordx4 v[194:197], v17, s[0:1] offset:256
	global_load_dwordx4 v[198:201], v18, s[0:1] offset:256
	global_load_dwordx4 v[202:205], v19, s[0:1] offset:256
	s_waitcnt vmcnt(32)
	v_mov_b32_e32 v31, 0x358637bd
	v_fmamk_f32 v24, v24, 0x3a000000, v31
	v_fmamk_f32 v25, v25, 0x3a000000, v31
	v_fmamk_f32 v26, v26, 0x3a000000, v31
	v_fmamk_f32 v27, v27, 0x3a000000, v31
	s_mov_b32 s20, 0x800000
	v_mul_f32_e32 v31, 0x4b800000, v24
	v_cmp_gt_f32_e32 vcc, s20, v24
	s_nop 1
	v_cndmask_b32_e32 v24, v24, v31, vcc
	v_rsq_f32_e32 v24, v24
	s_nop 0
	v_mul_f32_e32 v31, 0x45800000, v24
	v_cndmask_b32_e32 v24, v24, v31, vcc
	v_mul_f32_e32 v31, 0x4b800000, v25
	v_cmp_gt_f32_e32 vcc, s20, v25
	s_nop 1
	v_cndmask_b32_e32 v25, v25, v31, vcc
	v_rsq_f32_e32 v25, v25
	s_nop 0
	v_mul_f32_e32 v31, 0x45800000, v25
	v_cndmask_b32_e32 v25, v25, v31, vcc
	v_mul_f32_e32 v31, 0x4b800000, v26
	v_cmp_gt_f32_e32 vcc, s20, v26
	s_nop 1
	v_cndmask_b32_e32 v26, v26, v31, vcc
	v_rsq_f32_e32 v26, v26
	s_nop 0
	v_mul_f32_e32 v31, 0x45800000, v26
	v_cndmask_b32_e32 v26, v26, v31, vcc
	v_mul_f32_e32 v31, 0x4b800000, v27
	v_cmp_gt_f32_e32 vcc, s20, v27
	s_nop 1
	v_cndmask_b32_e32 v27, v27, v31, vcc
	v_rsq_f32_e32 v27, v27
	s_nop 0
	v_mul_f32_e32 v31, 0x45800000, v27
	v_cndmask_b32_e32 v27, v27, v31, vcc
	s_waitcnt vmcnt(19)
	v_mfma_f32_16x16x32_bf16 v[0:3], v[32:35], v[80:83], 0
	global_load_dwordx4 v[80:83], v16, s[0:1] offset:320
	s_waitcnt vmcnt(19)
	v_mfma_f32_16x16x32_bf16 v[4:7], v[32:35], v[84:87], 0
	global_load_dwordx4 v[84:87], v17, s[0:1] offset:320
	s_waitcnt vmcnt(19)
	v_mfma_f32_16x16x32_bf16 v[8:11], v[32:35], v[88:91], 0
	global_load_dwordx4 v[88:91], v18, s[0:1] offset:320
	s_waitcnt vmcnt(19)
	v_mfma_f32_16x16x32_bf16 v[12:15], v[32:35], v[92:95], 0
	global_load_dwordx4 v[92:95], v19, s[0:1] offset:320
	s_waitcnt vmcnt(19)
	v_mfma_f32_16x16x32_bf16 v[0:3], v[36:39], v[96:99], v[0:3]
	global_load_dwordx4 v[96:99], v16, s[0:1] offset:384
	s_waitcnt vmcnt(19)
	v_mfma_f32_16x16x32_bf16 v[4:7], v[36:39], v[100:103], v[4:7]
	global_load_dwordx4 v[100:103], v17, s[0:1] offset:384
	s_waitcnt vmcnt(19)
	v_mfma_f32_16x16x32_bf16 v[8:11], v[36:39], v[104:107], v[8:11]
	global_load_dwordx4 v[104:107], v18, s[0:1] offset:384
	s_waitcnt vmcnt(19)
	v_mfma_f32_16x16x32_bf16 v[12:15], v[36:39], v[108:111], v[12:15]
	global_load_dwordx4 v[108:111], v19, s[0:1] offset:384
	s_waitcnt vmcnt(19)
	v_mfma_f32_16x16x32_bf16 v[0:3], v[40:43], v[112:115], v[0:3]
	global_load_dwordx4 v[112:115], v16, s[0:1] offset:448
	s_waitcnt vmcnt(19)
	v_mfma_f32_16x16x32_bf16 v[4:7], v[40:43], v[116:119], v[4:7]
	global_load_dwordx4 v[116:119], v17, s[0:1] offset:448
	s_waitcnt vmcnt(19)
	v_mfma_f32_16x16x32_bf16 v[8:11], v[40:43], v[120:123], v[8:11]
	global_load_dwordx4 v[120:123], v18, s[0:1] offset:448
	s_waitcnt vmcnt(19)
	v_mfma_f32_16x16x32_bf16 v[12:15], v[40:43], v[124:127], v[12:15]
	global_load_dwordx4 v[124:127], v19, s[0:1] offset:448
	s_waitcnt vmcnt(19)
	v_mfma_f32_16x16x32_bf16 v[0:3], v[44:47], v[174:177], v[0:3]
	global_load_dwordx4 v[174:177], v16, s[0:1] offset:512
	s_waitcnt vmcnt(19)
	v_mfma_f32_16x16x32_bf16 v[4:7], v[44:47], v[178:181], v[4:7]
	global_load_dwordx4 v[178:181], v17, s[0:1] offset:512
	s_waitcnt vmcnt(19)
	v_mfma_f32_16x16x32_bf16 v[8:11], v[44:47], v[182:185], v[8:11]
	global_load_dwordx4 v[182:185], v18, s[0:1] offset:512
	s_waitcnt vmcnt(19)
	v_mfma_f32_16x16x32_bf16 v[12:15], v[44:47], v[186:189], v[12:15]
	global_load_dwordx4 v[186:189], v19, s[0:1] offset:512
	s_cmp_eq_u32 s13, 5
	s_cbranch_scc0 .Lsk_p3_nomid
	s_nop 7
	s_nop 3
	v_mul_f32_e32 v0, v0, v24
	v_mul_f32_e32 v1, v1, v24
	v_mul_f32_e32 v2, v2, v24
	v_mul_f32_e32 v3, v3, v24
	v_mul_f32_e32 v4, v4, v25
	v_mul_f32_e32 v5, v5, v25
	v_mul_f32_e32 v6, v6, v25
	v_mul_f32_e32 v7, v7, v25
	v_mul_f32_e32 v8, v8, v26
	v_mul_f32_e32 v9, v9, v26
	v_mul_f32_e32 v10, v10, v26
	v_mul_f32_e32 v11, v11, v26
	v_mul_f32_e32 v12, v12, v27
	v_mul_f32_e32 v13, v13, v27
	v_mul_f32_e32 v14, v14, v27
	v_mul_f32_e32 v15, v15, v27
	s_nop 1
.Lsk_p3_nomid:
	s_waitcnt vmcnt(19)
	v_mfma_f32_16x16x32_bf16 v[0:3], v[48:51], v[190:193], v[0:3]
	global_load_dwordx4 v[190:193], v16, s[0:1] offset:576
	s_waitcnt vmcnt(19)
	v_mfma_f32_16x16x32_bf16 v[4:7], v[48:51], v[194:197], v[4:7]
	global_load_dwordx4 v[194:197], v17, s[0:1] offset:576
	s_waitcnt vmcnt(19)
	v_mfma_f32_16x16x32_bf16 v[8:11], v[48:51], v[198:201], v[8:11]
	global_load_dwordx4 v[198:201], v18, s[0:1] offset:576
	s_waitcnt vmcnt(19)
	v_mfma_f32_16x16x32_bf16 v[12:15], v[48:51], v[202:205], v[12:15]
	global_load_dwordx4 v[202:205], v19, s[0:1] offset:576
	s_waitcnt vmcnt(19)
	v_mfma_f32_16x16x32_bf16 v[0:3], v[52:55], v[80:83], v[0:3]
	global_load_dwordx4 v[80:83], v16, s[0:1] offset:640
	s_waitcnt vmcnt(19)
	v_mfma_f32_16x16x32_bf16 v[4:7], v[52:55], v[84:87], v[4:7]
	global_load_dwordx4 v[84:87], v17, s[0:1] offset:640
	s_waitcnt vmcnt(19)
	v_mfma_f32_16x16x32_bf16 v[8:11], v[52:55], v[88:91], v[8:11]
	global_load_dwordx4 v[88:91], v18, s[0:1] offset:640
	s_waitcnt vmcnt(19)
	v_mfma_f32_16x16x32_bf16 v[12:15], v[52:55], v[92:95], v[12:15]
	global_load_dwordx4 v[92:95], v19, s[0:1] offset:640
	s_waitcnt vmcnt(19)
	v_mfma_f32_16x16x32_bf16 v[0:3], v[56:59], v[96:99], v[0:3]
	global_load_dwordx4 v[96:99], v16, s[0:1] offset:704
	s_waitcnt vmcnt(19)
	v_mfma_f32_16x16x32_bf16 v[4:7], v[56:59], v[100:103], v[4:7]
	global_load_dwordx4 v[100:103], v17, s[0:1] offset:704
	s_waitcnt vmcnt(19)
	v_mfma_f32_16x16x32_bf16 v[8:11], v[56:59], v[104:107], v[8:11]
	global_load_dwordx4 v[104:107], v18, s[0:1] offset:704
	s_waitcnt vmcnt(19)
	v_mfma_f32_16x16x32_bf16 v[12:15], v[56:59], v[108:111], v[12:15]
	global_load_dwordx4 v[108:111], v19, s[0:1] offset:704
	s_waitcnt vmcnt(19)
	v_mfma_f32_16x16x32_bf16 v[0:3], v[60:63], v[112:115], v[0:3]
	s_waitcnt vmcnt(18)
	v_mfma_f32_16x16x32_bf16 v[4:7], v[60:63], v[116:119], v[4:7]
	s_waitcnt vmcnt(17)
	v_mfma_f32_16x16x32_bf16 v[8:11], v[60:63], v[120:123], v[8:11]
	s_waitcnt vmcnt(16)
	v_mfma_f32_16x16x32_bf16 v[12:15], v[60:63], v[124:127], v[12:15]
	s_waitcnt vmcnt(15)
	v_mfma_f32_16x16x32_bf16 v[0:3], v[64:67], v[174:177], v[0:3]
	s_waitcnt vmcnt(14)
	v_mfma_f32_16x16x32_bf16 v[4:7], v[64:67], v[178:181], v[4:7]
	s_waitcnt vmcnt(13)
	v_mfma_f32_16x16x32_bf16 v[8:11], v[64:67], v[182:185], v[8:11]
	s_waitcnt vmcnt(12)
	v_mfma_f32_16x16x32_bf16 v[12:15], v[64:67], v[186:189], v[12:15]
	s_waitcnt vmcnt(11)
	v_mfma_f32_16x16x32_bf16 v[0:3], v[68:71], v[190:193], v[0:3]
	s_waitcnt vmcnt(10)
	v_mfma_f32_16x16x32_bf16 v[4:7], v[68:71], v[194:197], v[4:7]
	s_waitcnt vmcnt(9)
	v_mfma_f32_16x16x32_bf16 v[8:11], v[68:71], v[198:201], v[8:11]
	s_waitcnt vmcnt(8)
	v_mfma_f32_16x16x32_bf16 v[12:15], v[68:71], v[202:205], v[12:15]
	s_waitcnt vmcnt(7)
	v_mfma_f32_16x16x32_bf16 v[0:3], v[72:75], v[80:83], v[0:3]
	s_waitcnt vmcnt(6)
	v_mfma_f32_16x16x32_bf16 v[4:7], v[72:75], v[84:87], v[4:7]
	s_waitcnt vmcnt(5)
	v_mfma_f32_16x16x32_bf16 v[8:11], v[72:75], v[88:91], v[8:11]
	s_waitcnt vmcnt(4)
	v_mfma_f32_16x16x32_bf16 v[12:15], v[72:75], v[92:95], v[12:15]
	s_waitcnt vmcnt(3)
	v_mfma_f32_16x16x32_bf16 v[0:3], v[76:79], v[96:99], v[0:3]
	s_waitcnt vmcnt(2)
	v_mfma_f32_16x16x32_bf16 v[4:7], v[76:79], v[100:103], v[4:7]
	s_waitcnt vmcnt(1)
	v_mfma_f32_16x16x32_bf16 v[8:11], v[76:79], v[104:107], v[8:11]
	s_waitcnt vmcnt(0)
	v_mfma_f32_16x16x32_bf16 v[12:15], v[76:79], v[108:111], v[12:15]
	s_cmp_lt_u32 s13, 5
	s_cbranch_scc0 .Lsk_p3_noend
	s_nop 7
	s_nop 3
	v_mul_f32_e32 v0, v0, v24
	v_mul_f32_e32 v1, v1, v24
	v_mul_f32_e32 v2, v2, v24
	v_mul_f32_e32 v3, v3, v24
	v_mul_f32_e32 v4, v4, v25
	v_mul_f32_e32 v5, v5, v25
	v_mul_f32_e32 v6, v6, v25
	v_mul_f32_e32 v7, v7, v25
	v_mul_f32_e32 v8, v8, v26
	v_mul_f32_e32 v9, v9, v26
	v_mul_f32_e32 v10, v10, v26
	v_mul_f32_e32 v11, v11, v26
	v_mul_f32_e32 v12, v12, v27
	v_mul_f32_e32 v13, v13, v27
	v_mul_f32_e32 v14, v14, v27
	v_mul_f32_e32 v15, v15, v27
	s_nop 1
.Lsk_p3_noend:
	s_lshl_b32 s20, s13, 12
	v_lshl_add_u32 v31, v23, 4, s20
	s_nop 7
	s_nop 3
	ds_write_b128 v31, v[0:3]
	ds_write_b128 v31, v[4:7] offset:1024
	ds_write_b128 v31, v[8:11] offset:2048
	ds_write_b128 v31, v[12:15] offset:3072
	s_lshl_b32 s20, s19, 6
	s_lshl_b32 s21, s13, 4
	s_add_i32 s20, s20, s21
	v_add_u32_e32 v28, s20, v21
	s_lshl_b32 s21, s18, 4
	v_lshl_add_u32 v29, v22, 2, s21
	v_lshl_add_u32 v29, v28, 11, v29
	s_lshl_b32 s20, s13, 10
	v_lshl_add_u32 v30, v23, 4, s20
	s_waitcnt lgkmcnt(0)
	s_barrier
	s_cmp_lt_u32 s13, 4
	s_cbranch_scc0 .Lsk_p3_skip
	v_lshlrev_b32_e32 v64, 2, v29
	global_load_dwordx4 v[68:71], v64, s[6:7]
	v_lshlrev_b32_e32 v65, 1, v29
	ds_read_b128 v[32:35], v30
	ds_read_b128 v[36:39], v30 offset:4096
	ds_read_b128 v[40:43], v30 offset:8192
	ds_read_b128 v[44:47], v30 offset:12288
	ds_read_b128 v[48:51], v30 offset:16384
	ds_read_b128 v[52:55], v30 offset:20480
	ds_read_b128 v[56:59], v30 offset:24576
	ds_read_b128 v[60:63], v30 offset:28672
	s_waitcnt lgkmcnt(7)
	v_pk_add_f32 v[34:35], v[34:35], 0 op_sel_hi:[1,0]
	v_pk_add_f32 v[32:33], v[32:33], 0 op_sel_hi:[1,0]
	s_waitcnt lgkmcnt(6)
	v_pk_add_f32 v[34:35], v[34:35], v[38:39]
	v_pk_add_f32 v[32:33], v[32:33], v[36:37]
	s_waitcnt lgkmcnt(5)
	v_pk_add_f32 v[34:35], v[34:35], v[42:43]
	v_pk_add_f32 v[32:33], v[32:33], v[40:41]
	s_waitcnt lgkmcnt(4)
	v_pk_add_f32 v[34:35], v[34:35], v[46:47]
	v_pk_add_f32 v[32:33], v[32:33], v[44:45]
	s_waitcnt lgkmcnt(3)
	v_pk_add_f32 v[34:35], v[34:35], v[50:51]
	v_pk_add_f32 v[32:33], v[32:33], v[48:49]
	s_waitcnt lgkmcnt(2)
	v_pk_add_f32 v[34:35], v[34:35], v[54:55]
	v_pk_add_f32 v[32:33], v[32:33], v[52:53]
	s_waitcnt lgkmcnt(1)
	v_pk_add_f32 v[34:35], v[34:35], v[58:59]
	v_pk_add_f32 v[32:33], v[32:33], v[56:57]
	s_waitcnt lgkmcnt(0)
	v_pk_add_f32 v[34:35], v[34:35], v[62:63]
	v_pk_add_f32 v[32:33], v[32:33], v[60:61]
	s_waitcnt vmcnt(0)
	v_pk_add_f32 v[34:35], v[34:35], v[70:71]
	v_pk_add_f32 v[32:33], v[32:33], v[68:69]
	v_mul_f32_e32 v75, v35, v35
	v_mul_f32_e32 v74, v33, v33
	v_fmac_f32_e32 v74, v32, v32
	v_fmac_f32_e32 v75, v34, v34
	v_add_f32_e32 v76, v74, v75
	v_xor_b32_e32 v77, 16, v23
	v_lshlrev_b32_e32 v77, 2, v77
	ds_bpermute_b32 v78, v77, v76
	v_cvt_pk_bf16_f32 v80, v32, v33
	v_cvt_pk_bf16_f32 v81, v34, v35
	v_xor_b32_e32 v79, 32, v23
	v_lshlrev_b32_e32 v79, 2, v79
	s_waitcnt lgkmcnt(0)
	v_add_f32_e32 v76, v76, v78
	ds_bpermute_b32 v78, v79, v76
	global_store_dwordx2 v65, v[80:81], s[8:9]
	v_lshlrev_b32_e32 v82, 2, v28
	v_cmp_gt_u32_e32 vcc, 16, v23
	s_waitcnt lgkmcnt(0)
	v_add_f32_e32 v76, v76, v78
	s_and_saveexec_b64 s[10:11], vcc
	s_add_u32 s4, s92, 0x10400
	s_addc_u32 s5, s93, 0
	s_nop 0
	global_atomic_add_f32 v82, v76, s[4:5]
	s_add_u32 s4, s92, 0x8000
	s_addc_u32 s5, s93, 0
	s_mov_b64 exec, s[10:11]
.Lsk_p3_skip:
	s_barrier
	s_add_i32 s12, s12, s96
	s_branch .Lsk_p3_loop
.Lsk_p3_done:
.LBB0_697:
	s_cmp_gt_i32 s95, 4
	s_cselect_b64 s[0:1], -1, 0
	s_and_b64 s[2:3], s[14:15], s[0:1]
	v_readlane_b32 s48, v237, 0
	s_andn2_b64 vcc, exec, s[2:3]
	v_readlane_b32 s52, v237, 4
	v_readlane_b32 s53, v237, 5
	v_readlane_b32 s54, v237, 6
	v_readlane_b32 s55, v237, 7
	v_readlane_b32 s49, v237, 1
	v_readlane_b32 s50, v237, 2
	v_readlane_b32 s51, v237, 3
	s_cbranch_vccnz .LBB0_751
	s_waitcnt vmcnt(0)
	s_waitcnt vmcnt(0) lgkmcnt(0)
	s_barrier
	s_mov_b64 s[2:3], exec
	v_readlane_b32 s4, v237, 10
	v_readlane_b32 s5, v237, 11
	s_and_b64 s[4:5], s[2:3], s[4:5]
	s_mov_b64 exec, s[4:5]
	s_cbranch_execz .LBB0_750
	s_add_i32 s4, 0, 0x23fc0
	v_mov_b32_e32 v0, s4
	s_waitcnt vmcnt(0) expcnt(0) lgkmcnt(0)
	ds_read_b32 v2, v0
	s_add_i32 s4, 0, 0x23fc4
	v_mov_b32_e32 v0, s4
	ds_read_b32 v0, v0
	s_waitcnt lgkmcnt(1)
	v_cmp_ne_u32_e32 vcc, 0, v2
	s_cbranch_vccnz .LBB0_714
	v_readlane_b32 s4, v237, 8
	s_mul_i32 s33, s97, s4
	s_add_u32 s4, s92, 0x80200
	s_addc_u32 s5, s93, 0
	s_add_u32 s6, s92, 0x80400
	s_addc_u32 s7, s93, 0
	s_add_u32 s8, s92, 0x80500
	s_addc_u32 s9, s93, 0
	s_add_u32 s10, s92, 0x80600
	s_addc_u32 s11, s93, 0
	s_add_u32 s12, s92, 0x80700
	s_addc_u32 s13, s93, 0
	s_add_u32 s14, s92, 0x80800
	s_addc_u32 s15, s93, 0
	s_add_u32 s16, s92, 0x80900
	s_addc_u32 s17, s93, 0
	s_add_u32 s18, s92, 0x80a00
	s_addc_u32 s19, s93, 0
	s_add_u32 s20, s92, 0x80b00
	s_addc_u32 s21, s93, 0
	s_add_u32 s22, s92, 0x80c00
	s_addc_u32 s23, s93, 0
	s_add_u32 s24, s92, 0x80d00
	s_addc_u32 s25, s93, 0
	s_add_u32 s26, s92, 0x80e00
	s_addc_u32 s27, s93, 0
	s_add_u32 s28, s92, 0x80f00
	s_addc_u32 s29, s93, 0
	s_add_u32 s30, s92, 0x81000
	s_addc_u32 s31, s93, 0
	s_add_u32 s34, s92, 0x81100
	s_addc_u32 s35, s93, 0
	s_add_u32 s38, s92, 0x81200
	s_addc_u32 s39, s93, 0
	s_add_u32 s40, s92, 0x81300
	s_mul_i32 s33, s33, s96
	s_addc_u32 s41, s93, 0
	s_mov_b32 s48, 1
	v_mov_b32_e32 v16, 0
	s_branch .LBB0_702

.LBB0_1006:
	s_waitcnt vmcnt(0)
	s_barrier
	v_and_b32_e32 v23, 63, v172
	v_and_b32_e32 v21, 15, v172
	v_bfe_u32 v22, v172, 4, 2
	v_readfirstlane_b32 s22, v172
	s_add_u32 s0, s92, 0xea00000
	s_addc_u32 s1, s93, 0
	s_add_u32 s4, s92, 0x2e00000
	s_addc_u32 s5, s93, 0
	s_lshr_b32 s19, s22, 6
	s_mov_b32 s18, s76
	s_add_u32 s12, s92, 0x9200000
	s_addc_u32 s13, s93, 0
	s_add_u32 s14, s92, 0x18800
	s_addc_u32 s15, s93, 0
.Lsk_p6_loop:
	s_cmpk_lt_i32 s18, 0x100
	s_cbranch_scc0 .Lsk_p6_done
	s_and_b32 s20, s18, 7
	s_lshr_b32 s22, s18, 4
	s_lshl_b32 s22, s22, 3
	s_or_b32 s20, s20, s22
	s_bfe_u32 s21, s18, 0x10003
	s_lshl_b32 s22, s21, 6
	v_add_u32_e32 v28, s22, v21
	s_mul_i32 s23, s19, 0x80
	v_mul_u32_u24_e32 v16, 0x400, v28
	v_add_u32_e32 v16, s23, v16
	v_lshl_add_u32 v16, v22, 4, v16
	v_add_u32_e32 v17, 0x4000, v16
	v_add_u32_e32 v18, 0x8000, v16
	v_add_u32_e32 v19, 0xc000, v16
	s_lshl_b32 s22, s20, 4
	v_add_u32_e32 v29, s22, v21
	v_mul_u32_u24_e32 v20, 0x400, v29
	v_add_u32_e32 v20, s23, v20
	v_lshl_add_u32 v20, v22, 4, v20
	global_load_dwordx4 v[32:35], v20, s[4:5] offset:0
	global_load_dwordx4 v[36:39], v20, s[4:5] offset:64
	global_load_dwordx4 v[80:83], v16, s[0:1] offset:0
	global_load_dwordx4 v[84:87], v17, s[0:1] offset:0
	global_load_dwordx4 v[88:91], v18, s[0:1] offset:0
	global_load_dwordx4 v[92:95], v19, s[0:1] offset:0
	global_load_dwordx4 v[96:99], v16, s[0:1] offset:64
	global_load_dwordx4 v[100:103], v17, s[0:1] offset:64
	global_load_dwordx4 v[104:107], v18, s[0:1] offset:64
	global_load_dwordx4 v[108:111], v19, s[0:1] offset:64
	s_waitcnt vmcnt(7)
	v_mfma_f32_16x16x32_bf16 v[0:3], v[32:35], v[80:83], 0
	s_waitcnt vmcnt(6)
	v_mfma_f32_16x16x32_bf16 v[4:7], v[32:35], v[84:87], 0
	s_waitcnt vmcnt(5)
	v_mfma_f32_16x16x32_bf16 v[8:11], v[32:35], v[88:91], 0
	s_waitcnt vmcnt(4)
	v_mfma_f32_16x16x32_bf16 v[12:15], v[32:35], v[92:95], 0
	s_waitcnt vmcnt(3)
	v_mfma_f32_16x16x32_bf16 v[0:3], v[36:39], v[96:99], v[0:3]
	s_waitcnt vmcnt(2)
	v_mfma_f32_16x16x32_bf16 v[4:7], v[36:39], v[100:103], v[4:7]
	s_waitcnt vmcnt(1)
	v_mfma_f32_16x16x32_bf16 v[8:11], v[36:39], v[104:107], v[8:11]
	s_waitcnt vmcnt(0)
	v_mfma_f32_16x16x32_bf16 v[12:15], v[36:39], v[108:111], v[12:15]
	s_lshl_b32 s22, s19, 12
	v_lshl_add_u32 v31, v23, 4, s22
	s_nop 7
	s_nop 3
	ds_write_b128 v31, v[0:3]
	ds_write_b128 v31, v[4:7] offset:1024
	ds_write_b128 v31, v[8:11] offset:2048
	ds_write_b128 v31, v[12:15] offset:3072
	s_lshl_b32 s22, s21, 6
	s_lshl_b32 s23, s19, 4
	s_add_i32 s22, s22, s23
	v_add_u32_e32 v28, s22, v21
	s_lshl_b32 s23, s20, 4
	v_lshl_add_u32 v29, v22, 2, s23
	v_lshl_add_u32 v29, v28, 11, v29
	s_lshl_b32 s22, s19, 10
	v_lshl_add_u32 v30, v23, 4, s22
	s_waitcnt lgkmcnt(0)
	s_barrier
	s_cmp_lt_u32 s19, 4
	s_cbranch_scc0 .Lsk_p6_skip
	v_lshlrev_b32_e32 v65, 1, v29
	global_load_dwordx2 v[72:73], v65, s[12:13]
	v_lshlrev_b32_e32 v64, 2, v29
	ds_read_b128 v[32:35], v30
	ds_read_b128 v[36:39], v30 offset:4096
	ds_read_b128 v[40:43], v30 offset:8192
	ds_read_b128 v[44:47], v30 offset:12288
	ds_read_b128 v[48:51], v30 offset:16384
	ds_read_b128 v[52:55], v30 offset:20480
	ds_read_b128 v[56:59], v30 offset:24576
	ds_read_b128 v[60:63], v30 offset:28672
	s_waitcnt lgkmcnt(7)
	v_pk_add_f32 v[34:35], v[34:35], 0 op_sel_hi:[1,0]
	v_pk_add_f32 v[32:33], v[32:33], 0 op_sel_hi:[1,0]
	s_waitcnt lgkmcnt(6)
	v_pk_add_f32 v[34:35], v[34:35], v[38:39]
	v_pk_add_f32 v[32:33], v[32:33], v[36:37]
	s_waitcnt lgkmcnt(5)
	v_pk_add_f32 v[34:35], v[34:35], v[42:43]
	v_pk_add_f32 v[32:33], v[32:33], v[40:41]
	s_waitcnt lgkmcnt(4)
	v_pk_add_f32 v[34:35], v[34:35], v[46:47]
	v_pk_add_f32 v[32:33], v[32:33], v[44:45]
	s_waitcnt lgkmcnt(3)
	v_pk_add_f32 v[34:35], v[34:35], v[50:51]
	v_pk_add_f32 v[32:33], v[32:33], v[48:49]
	s_waitcnt lgkmcnt(2)
	v_pk_add_f32 v[34:35], v[34:35], v[54:55]
	v_pk_add_f32 v[32:33], v[32:33], v[52:53]
	s_waitcnt lgkmcnt(1)
	v_pk_add_f32 v[34:35], v[34:35], v[58:59]
	v_pk_add_f32 v[32:33], v[32:33], v[56:57]
	s_waitcnt lgkmcnt(0)
	v_pk_add_f32 v[34:35], v[34:35], v[62:63]
	v_pk_add_f32 v[32:33], v[32:33], v[60:61]
	s_waitcnt vmcnt(0)
	v_lshlrev_b32_e32 v68, 16, v72
	v_and_b32_e32 v69, 0xffff0000, v72
	v_lshlrev_b32_e32 v70, 16, v73
	v_and_b32_e32 v71, 0xffff0000, v73
	v_pk_add_f32 v[34:35], v[34:35], v[70:71]
	v_pk_add_f32 v[32:33], v[32:33], v[68:69]
	v_mul_f32_e32 v75, v35, v35
	v_mul_f32_e32 v74, v33, v33
	v_fmac_f32_e32 v74, v32, v32
	v_fmac_f32_e32 v75, v34, v34
	v_add_f32_e32 v76, v74, v75
	v_xor_b32_e32 v77, 16, v23
	v_lshlrev_b32_e32 v77, 2, v77
	ds_bpermute_b32 v78, v77, v76
	v_cvt_pk_bf16_f32 v80, v32, v33
	v_cvt_pk_bf16_f32 v81, v34, v35
	v_xor_b32_e32 v79, 32, v23
	v_lshlrev_b32_e32 v79, 2, v79
	s_waitcnt lgkmcnt(0)
	v_add_f32_e32 v76, v76, v78
	ds_bpermute_b32 v78, v79, v76
	global_store_dwordx2 v65, v[80:81], s[12:13]
	v_lshlrev_b32_e32 v82, 2, v28
	v_cmp_gt_u32_e32 vcc, 16, v23
	s_waitcnt lgkmcnt(0)
	v_add_f32_e32 v76, v76, v78
	s_and_saveexec_b64 s[16:17], vcc
	global_atomic_add_f32 v82, v76, s[14:15]
	s_mov_b64 exec, s[16:17]
.Lsk_p6_skip:
	s_barrier
	s_add_i32 s18, s18, s96
	s_branch .Lsk_p6_loop
.Lsk_p6_done:
.LBB0_1012:
	s_cmp_gt_i32 s95, 7
	s_cselect_b64 s[0:1], -1, 0
	s_and_b64 s[4:5], s[8:9], s[0:1]
	s_andn2_b64 vcc, exec, s[4:5]
	s_cbranch_vccnz .LBB0_1066
	s_waitcnt vmcnt(0)
	v_readlane_b32 s2, v237, 10
	v_readlane_b32 s3, v237, 11
	s_waitcnt vmcnt(0) lgkmcnt(0)
	s_barrier
	s_and_saveexec_b64 s[4:5], s[2:3]
	s_cbranch_execz .LBB0_1065
	s_add_i32 s6, 0, 0x23fc0
	v_mov_b32_e32 v0, s6
	s_waitcnt vmcnt(0) expcnt(0) lgkmcnt(0)
	ds_read_b32 v2, v0
	s_add_i32 s6, 0, 0x23fc4
	v_mov_b32_e32 v0, s6
	ds_read_b32 v0, v0
	s_waitcnt lgkmcnt(1)
	v_cmp_ne_u32_e32 vcc, 0, v2
	s_cbranch_vccnz .LBB0_1029
	s_add_u32 s6, s92, 0x80200
	s_addc_u32 s7, s93, 0
	s_add_u32 s8, s92, 0x80400
	s_addc_u32 s9, s93, 0
	s_add_u32 s10, s92, 0x80500
	s_addc_u32 s11, s93, 0
	s_add_u32 s12, s92, 0x80600
	s_addc_u32 s13, s93, 0
	s_add_u32 s14, s92, 0x80700
	s_addc_u32 s15, s93, 0
	s_add_u32 s16, s92, 0x80800
	s_addc_u32 s17, s93, 0
	s_add_u32 s18, s92, 0x80900
	s_addc_u32 s19, s93, 0
	s_add_u32 s20, s92, 0x80a00
	s_addc_u32 s21, s93, 0
	s_add_u32 s22, s92, 0x80b00
	s_addc_u32 s23, s93, 0
	s_add_u32 s24, s92, 0x80c00
	s_addc_u32 s25, s93, 0
	s_add_u32 s26, s92, 0x80d00
	s_addc_u32 s27, s93, 0
	s_add_u32 s28, s92, 0x80e00
	s_addc_u32 s29, s93, 0
	s_add_u32 s30, s92, 0x80f00
	s_addc_u32 s31, s93, 0
	s_add_u32 s34, s92, 0x81000
	s_addc_u32 s35, s93, 0
	s_add_u32 s38, s92, 0x81100
	s_addc_u32 s39, s93, 0
	s_add_u32 s40, s92, 0x81200
	v_readlane_b32 s2, v237, 8
	s_addc_u32 s41, s93, 0
	s_mul_i32 s33, s97, s2
	s_add_u32 s42, s92, 0x81300
	s_mul_i32 s33, s33, s96
	s_addc_u32 s43, s93, 0
	s_mov_b32 s50, 1
	v_mov_b32_e32 v16, 0
	s_branch .LBB0_1017

.LBB0_1372:
	s_waitcnt vmcnt(0)
	s_barrier
	v_and_b32_e32 v23, 63, v172
	v_and_b32_e32 v21, 15, v172
	v_bfe_u32 v22, v172, 4, 2
	v_readfirstlane_b32 s20, v172
	s_add_u32 s0, s92, 0x14500000
	s_addc_u32 s1, s93, 0
	s_add_u32 s2, s92, 0x5c00000
	s_addc_u32 s3, s93, 0
	s_lshr_b32 s17, s20, 6
	s_mov_b32 s16, s76
	s_add_u32 s10, s92, 0x9200000
	s_addc_u32 s11, s93, 0
	v_readlane_b32 s12, v237, 6
	v_readlane_b32 s13, v237, 7
	s_add_u32 s12, s12, 0x4000000
	s_addc_u32 s13, s13, 0
.Lsk_p9_loop:
	s_cmpk_lt_i32 s16, 0x100
	s_cbranch_scc0 .Lsk_p9_done
	s_and_b32 s18, s16, 7
	s_lshr_b32 s20, s16, 4
	s_lshl_b32 s20, s20, 3
	s_or_b32 s18, s18, s20
	s_bfe_u32 s19, s16, 0x10003
	s_lshl_b32 s20, s19, 6
	v_add_u32_e32 v28, s20, v21
	s_mul_i32 s21, s17, 0x580
	v_mul_u32_u24_e32 v16, 0x2c00, v28
	v_add_u32_e32 v16, s21, v16
	v_lshl_add_u32 v16, v22, 4, v16
	v_add_u32_e32 v17, 0x2c000, v16
	v_add_u32_e32 v18, 0x58000, v16
	v_add_u32_e32 v19, 0x84000, v16
	s_lshl_b32 s20, s18, 4
	v_add_u32_e32 v29, s20, v21
	v_mul_u32_u24_e32 v20, 0x2c00, v29
	v_add_u32_e32 v20, s21, v20
	v_lshl_add_u32 v20, v22, 4, v20
	global_load_dwordx4 v[32:35], v20, s[2:3] offset:0
	global_load_dwordx4 v[36:39], v20, s[2:3] offset:64
	global_load_dwordx4 v[40:43], v20, s[2:3] offset:128
	global_load_dwordx4 v[44:47], v20, s[2:3] offset:192
	global_load_dwordx4 v[48:51], v20, s[2:3] offset:256
	global_load_dwordx4 v[52:55], v20, s[2:3] offset:320
	global_load_dwordx4 v[56:59], v20, s[2:3] offset:384
	global_load_dwordx4 v[60:63], v20, s[2:3] offset:448
	global_load_dwordx4 v[64:67], v20, s[2:3] offset:512
	global_load_dwordx4 v[68:71], v20, s[2:3] offset:576
	global_load_dwordx4 v[72:75], v20, s[2:3] offset:640
	global_load_dwordx4 v[76:79], v20, s[2:3] offset:704
	global_load_dwordx4 v[80:83], v16, s[0:1] offset:0
	global_load_dwordx4 v[84:87], v17, s[0:1] offset:0
	global_load_dwordx4 v[88:91], v18, s[0:1] offset:0
	global_load_dwordx4 v[92:95], v19, s[0:1] offset:0
	global_load_dwordx4 v[96:99], v16, s[0:1] offset:64
	global_load_dwordx4 v[100:103], v17, s[0:1] offset:64
	global_load_dwordx4 v[104:107], v18, s[0:1] offset:64
	global_load_dwordx4 v[108:111], v19, s[0:1] offset:64
	global_load_dwordx4 v[112:115], v16, s[0:1] offset:128
	global_load_dwordx4 v[116:119], v17, s[0:1] offset:128
	global_load_dwordx4 v[120:123], v18, s[0:1] offset:128
	global_load_dwordx4 v[124:127], v19, s[0:1] offset:128
	global_load_dwordx4 v[174:177], v16, s[0:1] offset:192
	global_load_dwordx4 v[178:181], v17, s[0:1] offset:192
	global_load_dwordx4 v[182:185], v18, s[0:1] offset:192
	global_load_dwordx4 v[186:189], v19, s[0:1] offset:192
	global_load_dwordx4 v[190:193], v16, s[0:1] offset:256
	global_load_dwordx4 v[194:197], v17, s[0:1] offset:256
	global_load_dwordx4 v[198:201], v18, s[0:1] offset:256
	global_load_dwordx4 v[202:205], v19, s[0:1] offset:256
	s_waitcnt vmcnt(19)
	v_mfma_f32_16x16x32_bf16 v[0:3], v[32:35], v[80:83], 0
	global_load_dwordx4 v[80:83], v16, s[0:1] offset:320
	s_waitcnt vmcnt(19)
	v_mfma_f32_16x16x32_bf16 v[4:7], v[32:35], v[84:87], 0
	global_load_dwordx4 v[84:87], v17, s[0:1] offset:320
	s_waitcnt vmcnt(19)
	v_mfma_f32_16x16x32_bf16 v[8:11], v[32:35], v[88:91], 0
	global_load_dwordx4 v[88:91], v18, s[0:1] offset:320
	s_waitcnt vmcnt(19)
	v_mfma_f32_16x16x32_bf16 v[12:15], v[32:35], v[92:95], 0
	global_load_dwordx4 v[92:95], v19, s[0:1] offset:320
	global_load_dwordx4 v[32:35], v20, s[2:3] offset:768
	s_waitcnt vmcnt(20)
	v_mfma_f32_16x16x32_bf16 v[0:3], v[36:39], v[96:99], v[0:3]
	global_load_dwordx4 v[96:99], v16, s[0:1] offset:384
	s_waitcnt vmcnt(20)
	v_mfma_f32_16x16x32_bf16 v[4:7], v[36:39], v[100:103], v[4:7]
	global_load_dwordx4 v[100:103], v17, s[0:1] offset:384
	s_waitcnt vmcnt(20)
	v_mfma_f32_16x16x32_bf16 v[8:11], v[36:39], v[104:107], v[8:11]
	global_load_dwordx4 v[104:107], v18, s[0:1] offset:384
	s_waitcnt vmcnt(20)
	v_mfma_f32_16x16x32_bf16 v[12:15], v[36:39], v[108:111], v[12:15]
	global_load_dwordx4 v[108:111], v19, s[0:1] offset:384
	global_load_dwordx4 v[36:39], v20, s[2:3] offset:832
	s_waitcnt vmcnt(21)
	v_mfma_f32_16x16x32_bf16 v[0:3], v[40:43], v[112:115], v[0:3]
	global_load_dwordx4 v[112:115], v16, s[0:1] offset:448
	s_waitcnt vmcnt(21)
	v_mfma_f32_16x16x32_bf16 v[4:7], v[40:43], v[116:119], v[4:7]
	global_load_dwordx4 v[116:119], v17, s[0:1] offset:448
	s_waitcnt vmcnt(21)
	v_mfma_f32_16x16x32_bf16 v[8:11], v[40:43], v[120:123], v[8:11]
	global_load_dwordx4 v[120:123], v18, s[0:1] offset:448
	s_waitcnt vmcnt(21)
	v_mfma_f32_16x16x32_bf16 v[12:15], v[40:43], v[124:127], v[12:15]
	global_load_dwordx4 v[124:127], v19, s[0:1] offset:448
	global_load_dwordx4 v[40:43], v20, s[2:3] offset:896
	s_waitcnt vmcnt(22)
	v_mfma_f32_16x16x32_bf16 v[0:3], v[44:47], v[174:177], v[0:3]
	global_load_dwordx4 v[174:177], v16, s[0:1] offset:512
	s_waitcnt vmcnt(22)
	v_mfma_f32_16x16x32_bf16 v[4:7], v[44:47], v[178:181], v[4:7]
	global_load_dwordx4 v[178:181], v17, s[0:1] offset:512
	s_waitcnt vmcnt(22)
	v_mfma_f32_16x16x32_bf16 v[8:11], v[44:47], v[182:185], v[8:11]
	global_load_dwordx4 v[182:185], v18, s[0:1] offset:512
	s_waitcnt vmcnt(22)
	v_mfma_f32_16x16x32_bf16 v[12:15], v[44:47], v[186:189], v[12:15]
	global_load_dwordx4 v[186:189], v19, s[0:1] offset:512
	global_load_dwordx4 v[44:47], v20, s[2:3] offset:960
	s_waitcnt vmcnt(23)
	v_mfma_f32_16x16x32_bf16 v[0:3], v[48:51], v[190:193], v[0:3]
	global_load_dwordx4 v[190:193], v16, s[0:1] offset:576
	s_waitcnt vmcnt(23)
	v_mfma_f32_16x16x32_bf16 v[4:7], v[48:51], v[194:197], v[4:7]
	global_load_dwordx4 v[194:197], v17, s[0:1] offset:576
	s_waitcnt vmcnt(23)
	v_mfma_f32_16x16x32_bf16 v[8:11], v[48:51], v[198:201], v[8:11]
	global_load_dwordx4 v[198:201], v18, s[0:1] offset:576
	s_waitcnt vmcnt(23)
	v_mfma_f32_16x16x32_bf16 v[12:15], v[48:51], v[202:205], v[12:15]
	global_load_dwordx4 v[202:205], v19, s[0:1] offset:576
	global_load_dwordx4 v[48:51], v20, s[2:3] offset:1024
	s_waitcnt vmcnt(24)
	v_mfma_f32_16x16x32_bf16 v[0:3], v[52:55], v[80:83], v[0:3]
	global_load_dwordx4 v[80:83], v16, s[0:1] offset:640
	s_waitcnt vmcnt(24)
	v_mfma_f32_16x16x32_bf16 v[4:7], v[52:55], v[84:87], v[4:7]
	global_load_dwordx4 v[84:87], v17, s[0:1] offset:640
	s_waitcnt vmcnt(24)
	v_mfma_f32_16x16x32_bf16 v[8:11], v[52:55], v[88:91], v[8:11]
	global_load_dwordx4 v[88:91], v18, s[0:1] offset:640
	s_waitcnt vmcnt(24)
	v_mfma_f32_16x16x32_bf16 v[12:15], v[52:55], v[92:95], v[12:15]
	global_load_dwordx4 v[92:95], v19, s[0:1] offset:640
	global_load_dwordx4 v[52:55], v20, s[2:3] offset:1088
	s_waitcnt vmcnt(24)
	v_mfma_f32_16x16x32_bf16 v[0:3], v[56:59], v[96:99], v[0:3]
	global_load_dwordx4 v[96:99], v16, s[0:1] offset:704
	s_waitcnt vmcnt(24)
	v_mfma_f32_16x16x32_bf16 v[4:7], v[56:59], v[100:103], v[4:7]
	global_load_dwordx4 v[100:103], v17, s[0:1] offset:704
	s_waitcnt vmcnt(24)
	v_mfma_f32_16x16x32_bf16 v[8:11], v[56:59], v[104:107], v[8:11]
	global_load_dwordx4 v[104:107], v18, s[0:1] offset:704
	s_waitcnt vmcnt(24)
	v_mfma_f32_16x16x32_bf16 v[12:15], v[56:59], v[108:111], v[12:15]
	global_load_dwordx4 v[108:111], v19, s[0:1] offset:704
	global_load_dwordx4 v[56:59], v20, s[2:3] offset:1152
	s_waitcnt vmcnt(24)
	v_mfma_f32_16x16x32_bf16 v[0:3], v[60:63], v[112:115], v[0:3]
	global_load_dwordx4 v[112:115], v16, s[0:1] offset:768
	s_waitcnt vmcnt(24)
	v_mfma_f32_16x16x32_bf16 v[4:7], v[60:63], v[116:119], v[4:7]
	global_load_dwordx4 v[116:119], v17, s[0:1] offset:768
	s_waitcnt vmcnt(24)
	v_mfma_f32_16x16x32_bf16 v[8:11], v[60:63], v[120:123], v[8:11]
	global_load_dwordx4 v[120:123], v18, s[0:1] offset:768
	s_waitcnt vmcnt(24)
	v_mfma_f32_16x16x32_bf16 v[12:15], v[60:63], v[124:127], v[12:15]
	global_load_dwordx4 v[124:127], v19, s[0:1] offset:768
	global_load_dwordx4 v[60:63], v20, s[2:3] offset:1216
	s_waitcnt vmcnt(24)
	v_mfma_f32_16x16x32_bf16 v[0:3], v[64:67], v[174:177], v[0:3]
	global_load_dwordx4 v[174:177], v16, s[0:1] offset:832
	s_waitcnt vmcnt(24)
	v_mfma_f32_16x16x32_bf16 v[4:7], v[64:67], v[178:181], v[4:7]
	global_load_dwordx4 v[178:181], v17, s[0:1] offset:832
	s_waitcnt vmcnt(24)
	v_mfma_f32_16x16x32_bf16 v[8:11], v[64:67], v[182:185], v[8:11]
	global_load_dwordx4 v[182:185], v18, s[0:1] offset:832
	s_waitcnt vmcnt(24)
	v_mfma_f32_16x16x32_bf16 v[12:15], v[64:67], v[186:189], v[12:15]
	global_load_dwordx4 v[186:189], v19, s[0:1] offset:832
	global_load_dwordx4 v[64:67], v20, s[2:3] offset:1280
	s_waitcnt vmcnt(24)
	v_mfma_f32_16x16x32_bf16 v[0:3], v[68:71], v[190:193], v[0:3]
	global_load_dwordx4 v[190:193], v16, s[0:1] offset:896
	s_waitcnt vmcnt(24)
	v_mfma_f32_16x16x32_bf16 v[4:7], v[68:71], v[194:197], v[4:7]
	global_load_dwordx4 v[194:197], v17, s[0:1] offset:896
	s_waitcnt vmcnt(24)
	v_mfma_f32_16x16x32_bf16 v[8:11], v[68:71], v[198:201], v[8:11]
	global_load_dwordx4 v[198:201], v18, s[0:1] offset:896
	s_waitcnt vmcnt(24)
	v_mfma_f32_16x16x32_bf16 v[12:15], v[68:71], v[202:205], v[12:15]
	global_load_dwordx4 v[202:205], v19, s[0:1] offset:896
	global_load_dwordx4 v[68:71], v20, s[2:3] offset:1344
	s_waitcnt vmcnt(24)
	v_mfma_f32_16x16x32_bf16 v[0:3], v[72:75], v[80:83], v[0:3]
	global_load_dwordx4 v[80:83], v16, s[0:1] offset:960
	s_waitcnt vmcnt(24)
	v_mfma_f32_16x16x32_bf16 v[4:7], v[72:75], v[84:87], v[4:7]
	global_load_dwordx4 v[84:87], v17, s[0:1] offset:960
	s_waitcnt vmcnt(24)
	v_mfma_f32_16x16x32_bf16 v[8:11], v[72:75], v[88:91], v[8:11]
	global_load_dwordx4 v[88:91], v18, s[0:1] offset:960
	s_waitcnt vmcnt(24)
	v_mfma_f32_16x16x32_bf16 v[12:15], v[72:75], v[92:95], v[12:15]
	global_load_dwordx4 v[92:95], v19, s[0:1] offset:960
	s_waitcnt vmcnt(23)
	v_mfma_f32_16x16x32_bf16 v[0:3], v[76:79], v[96:99], v[0:3]
	global_load_dwordx4 v[96:99], v16, s[0:1] offset:1024
	s_waitcnt vmcnt(23)
	v_mfma_f32_16x16x32_bf16 v[4:7], v[76:79], v[100:103], v[4:7]
	global_load_dwordx4 v[100:103], v17, s[0:1] offset:1024
	s_waitcnt vmcnt(23)
	v_mfma_f32_16x16x32_bf16 v[8:11], v[76:79], v[104:107], v[8:11]
	global_load_dwordx4 v[104:107], v18, s[0:1] offset:1024
	s_waitcnt vmcnt(23)
	v_mfma_f32_16x16x32_bf16 v[12:15], v[76:79], v[108:111], v[12:15]
	global_load_dwordx4 v[108:111], v19, s[0:1] offset:1024
	s_waitcnt vmcnt(22)
	v_mfma_f32_16x16x32_bf16 v[0:3], v[32:35], v[112:115], v[0:3]
	global_load_dwordx4 v[112:115], v16, s[0:1] offset:1088
	s_waitcnt vmcnt(22)
	v_mfma_f32_16x16x32_bf16 v[4:7], v[32:35], v[116:119], v[4:7]
	global_load_dwordx4 v[116:119], v17, s[0:1] offset:1088
	s_waitcnt vmcnt(22)
	v_mfma_f32_16x16x32_bf16 v[8:11], v[32:35], v[120:123], v[8:11]
	global_load_dwordx4 v[120:123], v18, s[0:1] offset:1088
	s_waitcnt vmcnt(22)
	v_mfma_f32_16x16x32_bf16 v[12:15], v[32:35], v[124:127], v[12:15]
	global_load_dwordx4 v[124:127], v19, s[0:1] offset:1088
	s_waitcnt vmcnt(21)
	v_mfma_f32_16x16x32_bf16 v[0:3], v[36:39], v[174:177], v[0:3]
	global_load_dwordx4 v[174:177], v16, s[0:1] offset:1152
	s_waitcnt vmcnt(21)
	v_mfma_f32_16x16x32_bf16 v[4:7], v[36:39], v[178:181], v[4:7]
	global_load_dwordx4 v[178:181], v17, s[0:1] offset:1152
	s_waitcnt vmcnt(21)
	v_mfma_f32_16x16x32_bf16 v[8:11], v[36:39], v[182:185], v[8:11]
	global_load_dwordx4 v[182:185], v18, s[0:1] offset:1152
	s_waitcnt vmcnt(21)
	v_mfma_f32_16x16x32_bf16 v[12:15], v[36:39], v[186:189], v[12:15]
	global_load_dwordx4 v[186:189], v19, s[0:1] offset:1152
	s_waitcnt vmcnt(20)
	v_mfma_f32_16x16x32_bf16 v[0:3], v[40:43], v[190:193], v[0:3]
	global_load_dwordx4 v[190:193], v16, s[0:1] offset:1216
	s_waitcnt vmcnt(20)
	v_mfma_f32_16x16x32_bf16 v[4:7], v[40:43], v[194:197], v[4:7]
	global_load_dwordx4 v[194:197], v17, s[0:1] offset:1216
	s_waitcnt vmcnt(20)
	v_mfma_f32_16x16x32_bf16 v[8:11], v[40:43], v[198:201], v[8:11]
	global_load_dwordx4 v[198:201], v18, s[0:1] offset:1216
	s_waitcnt vmcnt(20)
	v_mfma_f32_16x16x32_bf16 v[12:15], v[40:43], v[202:205], v[12:15]
	global_load_dwordx4 v[202:205], v19, s[0:1] offset:1216
	s_waitcnt vmcnt(19)
	v_mfma_f32_16x16x32_bf16 v[0:3], v[44:47], v[80:83], v[0:3]
	global_load_dwordx4 v[80:83], v16, s[0:1] offset:1280
	s_waitcnt vmcnt(19)
	v_mfma_f32_16x16x32_bf16 v[4:7], v[44:47], v[84:87], v[4:7]
	global_load_dwordx4 v[84:87], v17, s[0:1] offset:1280
	s_waitcnt vmcnt(19)
	v_mfma_f32_16x16x32_bf16 v[8:11], v[44:47], v[88:91], v[8:11]
	global_load_dwordx4 v[88:91], v18, s[0:1] offset:1280
	s_waitcnt vmcnt(19)
	v_mfma_f32_16x16x32_bf16 v[12:15], v[44:47], v[92:95], v[12:15]
	global_load_dwordx4 v[92:95], v19, s[0:1] offset:1280
	s_waitcnt vmcnt(19)
	v_mfma_f32_16x16x32_bf16 v[0:3], v[48:51], v[96:99], v[0:3]
	global_load_dwordx4 v[96:99], v16, s[0:1] offset:1344
	s_waitcnt vmcnt(19)
	v_mfma_f32_16x16x32_bf16 v[4:7], v[48:51], v[100:103], v[4:7]
	global_load_dwordx4 v[100:103], v17, s[0:1] offset:1344
	s_waitcnt vmcnt(19)
	v_mfma_f32_16x16x32_bf16 v[8:11], v[48:51], v[104:107], v[8:11]
	global_load_dwordx4 v[104:107], v18, s[0:1] offset:1344
	s_waitcnt vmcnt(19)
	v_mfma_f32_16x16x32_bf16 v[12:15], v[48:51], v[108:111], v[12:15]
	global_load_dwordx4 v[108:111], v19, s[0:1] offset:1344
	s_waitcnt vmcnt(19)
	v_mfma_f32_16x16x32_bf16 v[0:3], v[52:55], v[112:115], v[0:3]
	s_waitcnt vmcnt(18)
	v_mfma_f32_16x16x32_bf16 v[4:7], v[52:55], v[116:119], v[4:7]
	s_waitcnt vmcnt(17)
	v_mfma_f32_16x16x32_bf16 v[8:11], v[52:55], v[120:123], v[8:11]
	s_waitcnt vmcnt(16)
	v_mfma_f32_16x16x32_bf16 v[12:15], v[52:55], v[124:127], v[12:15]
	s_waitcnt vmcnt(15)
	v_mfma_f32_16x16x32_bf16 v[0:3], v[56:59], v[174:177], v[0:3]
	s_waitcnt vmcnt(14)
	v_mfma_f32_16x16x32_bf16 v[4:7], v[56:59], v[178:181], v[4:7]
	s_waitcnt vmcnt(13)
	v_mfma_f32_16x16x32_bf16 v[8:11], v[56:59], v[182:185], v[8:11]
	s_waitcnt vmcnt(12)
	v_mfma_f32_16x16x32_bf16 v[12:15], v[56:59], v[186:189], v[12:15]
	s_waitcnt vmcnt(11)
	v_mfma_f32_16x16x32_bf16 v[0:3], v[60:63], v[190:193], v[0:3]
	s_waitcnt vmcnt(10)
	v_mfma_f32_16x16x32_bf16 v[4:7], v[60:63], v[194:197], v[4:7]
	s_waitcnt vmcnt(9)
	v_mfma_f32_16x16x32_bf16 v[8:11], v[60:63], v[198:201], v[8:11]
	s_waitcnt vmcnt(8)
	v_mfma_f32_16x16x32_bf16 v[12:15], v[60:63], v[202:205], v[12:15]
	s_waitcnt vmcnt(7)
	v_mfma_f32_16x16x32_bf16 v[0:3], v[64:67], v[80:83], v[0:3]
	s_waitcnt vmcnt(6)
	v_mfma_f32_16x16x32_bf16 v[4:7], v[64:67], v[84:87], v[4:7]
	s_waitcnt vmcnt(5)
	v_mfma_f32_16x16x32_bf16 v[8:11], v[64:67], v[88:91], v[8:11]
	s_waitcnt vmcnt(4)
	v_mfma_f32_16x16x32_bf16 v[12:15], v[64:67], v[92:95], v[12:15]
	s_waitcnt vmcnt(3)
	v_mfma_f32_16x16x32_bf16 v[0:3], v[68:71], v[96:99], v[0:3]
	s_waitcnt vmcnt(2)
	v_mfma_f32_16x16x32_bf16 v[4:7], v[68:71], v[100:103], v[4:7]
	s_waitcnt vmcnt(1)
	v_mfma_f32_16x16x32_bf16 v[8:11], v[68:71], v[104:107], v[8:11]
	s_waitcnt vmcnt(0)
	v_mfma_f32_16x16x32_bf16 v[12:15], v[68:71], v[108:111], v[12:15]
	s_lshl_b32 s20, s17, 12
	v_lshl_add_u32 v31, v23, 4, s20
	s_nop 7
	s_nop 3
	ds_write_b128 v31, v[0:3]
	ds_write_b128 v31, v[4:7] offset:1024
	ds_write_b128 v31, v[8:11] offset:2048
	ds_write_b128 v31, v[12:15] offset:3072
	s_lshl_b32 s20, s19, 6
	s_lshl_b32 s21, s17, 4
	s_add_i32 s20, s20, s21
	v_add_u32_e32 v28, s20, v21
	s_lshl_b32 s21, s18, 4
	v_lshl_add_u32 v29, v22, 2, s21
	v_lshl_add_u32 v29, v28, 11, v29
	s_lshl_b32 s20, s17, 10
	v_lshl_add_u32 v30, v23, 4, s20
	s_waitcnt lgkmcnt(0)
	s_barrier
	s_cmp_lt_u32 s17, 4
	s_cbranch_scc0 .Lsk_p9_skip
	v_lshlrev_b32_e32 v65, 1, v29
	global_load_dwordx2 v[72:73], v65, s[10:11]
	v_lshlrev_b32_e32 v64, 2, v29
	ds_read_b128 v[32:35], v30
	ds_read_b128 v[36:39], v30 offset:4096
	ds_read_b128 v[40:43], v30 offset:8192
	ds_read_b128 v[44:47], v30 offset:12288
	ds_read_b128 v[48:51], v30 offset:16384
	ds_read_b128 v[52:55], v30 offset:20480
	ds_read_b128 v[56:59], v30 offset:24576
	ds_read_b128 v[60:63], v30 offset:28672
	s_waitcnt lgkmcnt(7)
	v_pk_add_f32 v[34:35], v[34:35], 0 op_sel_hi:[1,0]
	v_pk_add_f32 v[32:33], v[32:33], 0 op_sel_hi:[1,0]
	s_waitcnt lgkmcnt(6)
	v_pk_add_f32 v[34:35], v[34:35], v[38:39]
	v_pk_add_f32 v[32:33], v[32:33], v[36:37]
	s_waitcnt lgkmcnt(5)
	v_pk_add_f32 v[34:35], v[34:35], v[42:43]
	v_pk_add_f32 v[32:33], v[32:33], v[40:41]
	s_waitcnt lgkmcnt(4)
	v_pk_add_f32 v[34:35], v[34:35], v[46:47]
	v_pk_add_f32 v[32:33], v[32:33], v[44:45]
	s_waitcnt lgkmcnt(3)
	v_pk_add_f32 v[34:35], v[34:35], v[50:51]
	v_pk_add_f32 v[32:33], v[32:33], v[48:49]
	s_waitcnt lgkmcnt(2)
	v_pk_add_f32 v[34:35], v[34:35], v[54:55]
	v_pk_add_f32 v[32:33], v[32:33], v[52:53]
	s_waitcnt lgkmcnt(1)
	v_pk_add_f32 v[34:35], v[34:35], v[58:59]
	v_pk_add_f32 v[32:33], v[32:33], v[56:57]
	s_waitcnt lgkmcnt(0)
	v_pk_add_f32 v[34:35], v[34:35], v[62:63]
	v_pk_add_f32 v[32:33], v[32:33], v[60:61]
	s_waitcnt vmcnt(0)
	v_lshlrev_b32_e32 v68, 16, v72
	v_and_b32_e32 v69, 0xffff0000, v72
	v_lshlrev_b32_e32 v70, 16, v73
	v_and_b32_e32 v71, 0xffff0000, v73
	v_pk_add_f32 v[34:35], v[34:35], v[70:71]
	v_pk_add_f32 v[32:33], v[32:33], v[68:69]
	global_store_dwordx4 v64, v[32:35], s[12:13]
.Lsk_p9_skip:
	s_barrier
	s_add_i32 s16, s16, s96
	s_branch .Lsk_p9_loop
.Lsk_p9_done:
.LBB0_1376:
	s_endpgm
